# prep gating: block-mean rows staged once per item in LDS, one dword per lane per block with next-row prefetch, element broadcast by v_readlane (same op order, bit-identical) instead of 16 uniform dwor
# speedup vs baseline: 1.0076x; 1.0043x over previous
; __device__ __forceinline__ float bflo(unsigned w) { return __uint_as_float(w << 16); }
; __device__ __forceinline__ float bfhi(unsigned w) { return __uint_as_float(w & 0xffff0000u); }
; __device__ __forceinline__ void prep_phase(const Args& a, LAS unsigned char* lds, int tid, int lane, int wave) {
;     ...
;     for (int wv = BID * NWAVES + wave; wv < Bn * 8 * (S / 64); wv += nwv) {
;         const int bh = __builtin_amdgcn_readfirstlane(wv / (S / 64)), t0 = __builtin_amdgcn_readfirstlane((wv % (S / 64)) * 64);
;         const int b = bh >> 3, h = bh & 7, t = t0 + lane, blk = t0 >> 8;
;         unsigned mask = 1u << blk;
;         if (blk > 0) {
;             float q[64];
;             const v4u* qp = (const v4u*)(Q + ((size_t)(b * S + t)) * D + h * 64);
; #pragma unroll
;             for (int c = 0; c < 8; ++c) { const v4u w = qp[c]; q[8 * c] = bflo(w.x); q[8 * c + 1] = bfhi(w.x); q[8 * c + 2] = bflo(w.y); q[8 * c + 3] = bfhi(w.y); q[8 * c + 4] = bflo(w.z); q[8 * c + 5] = bfhi(w.z); q[8 * c + 6] = bflo(w.w); q[8 * c + 7] = bfhi(w.w); }
;             float g0 = -3e38f, g1 = -3e38f, g2 = -3e38f; int i0 = -1, i1 = -1, i2 = -1;
;             for (int n = 0; n < blk; ++n) {
;                 const float* kb = KBAR + ((size_t)(bh * 32 + n)) * 64; float gsum = 0.f;
; #pragma unroll
;                 for (int d = 0; d < 64; ++d) gsum += q[d] * kb[d];
.LBB0_559:
	s_ashr_i32 s6, s3, 31
	s_lshr_b32 s6, s6, 25
	s_add_i32 s6, s3, s6
	s_ashr_i32 s12, s6, 7
	s_and_b32 s6, s6, 0xffffff80
	s_sub_i32 s10, s3, s6
	s_sub_i32 s98, 0x7f, s10
	s_cmpk_lt_i32 s3, 0x800
	s_cselect_b32 s10, s10, s98
	s_ashr_i32 s11, s10, 2
	s_lshl_b32 s13, 1, s11
	s_cmp_gt_i32 s11, 0
	v_lshl_or_b32 v0, s10, 6, v12
	s_cselect_b64 s[22:23], -1, 0
	s_cmp_lt_i32 s11, 1
	v_mov_b32_e32 v2, s13
	s_cbranch_scc1 .LBB0_570
	s_lshl_b32 s6, s12, 10
	s_and_b32 s6, s6, 0xffffe000
	v_add_u32_e32 v2, s6, v0
	s_waitcnt lgkmcnt(1)
	v_ashrrev_i32_e32 v3, 31, v2
	v_lshlrev_b64 v[2:3], 11, v[2:3]
	s_lshl_b32 s6, s12, 7
	v_lshl_add_u64 v[2:3], s[4:5], 0, v[2:3]
	s_and_b32 s6, s6, 0x380
	v_lshl_add_u64 v[10:11], v[2:3], 0, s[6:7]
	global_load_dwordx4 v[2:5], v[10:11], off
	global_load_dwordx4 v[6:9], v[10:11], off offset:16
	global_load_dwordx4 v[36:39], v[10:11], off offset:32
	global_load_dwordx4 v[46:49], v[10:11], off offset:48
	global_load_dwordx4 v[54:57], v[10:11], off offset:64
	global_load_dwordx4 v[62:65], v[10:11], off offset:80
	global_load_dwordx4 v[68:71], v[10:11], off offset:96
	global_load_dwordx4 v[72:75], v[10:11], off offset:112
	s_lshl_b32 s8, s12, 5
	s_ashr_i32 s9, s8, 31
	s_lshl_b64 s[8:9], s[8:9], 8
	s_add_u32 s24, s19, s8
	v_mov_b32_e32 v50, 0xff61b1e6
	v_mov_b32_e32 v44, -1
	s_addc_u32 s25, s20, s9
	v_and_b32_e32 v140, 63, v254
	v_lshlrev_b32_e32 v141, 4, v140
	v_add_u32_e32 v142, 0x1000, v141
	global_load_dwordx4 v[144:147], v141, s[24:25]
	global_load_dwordx4 v[148:151], v141, s[24:25] offset:1024
	global_load_dwordx4 v[152:155], v141, s[24:25] offset:2048
	global_load_dwordx4 v[156:159], v141, s[24:25] offset:3072
	global_load_dwordx4 v[160:163], v142, s[24:25]
	global_load_dwordx4 v[164:167], v142, s[24:25] offset:1024
	global_load_dwordx4 v[168:171], v142, s[24:25] offset:2048
	global_load_dwordx4 v[172:175], v142, s[24:25] offset:3072
	v_lshrrev_b32_e32 v143, 6, v254
	v_lshlrev_b32_e32 v143, 13, v143
	v_add_u32_e32 v140, v143, v141
	s_mov_b32 s6, 0
	s_waitcnt vmcnt(7) lgkmcnt(0)
	v_lshlrev_b32_e32 v1, 16, v2
	v_and_b32_e32 v17, 0xffff0000, v2
	v_lshlrev_b32_e32 v18, 16, v3
	v_and_b32_e32 v19, 0xffff0000, v3
	v_lshlrev_b32_e32 v20, 16, v4
	v_and_b32_e32 v21, 0xffff0000, v4
	v_lshlrev_b32_e32 v22, 16, v5
	v_and_b32_e32 v23, 0xffff0000, v5
	s_waitcnt vmcnt(6)
	v_lshlrev_b32_e32 v24, 16, v6
	v_and_b32_e32 v25, 0xffff0000, v6
	v_lshlrev_b32_e32 v26, 16, v7
	v_and_b32_e32 v27, 0xffff0000, v7
	v_lshlrev_b32_e32 v28, 16, v8
	v_and_b32_e32 v29, 0xffff0000, v8
	v_lshlrev_b32_e32 v30, 16, v9
	v_and_b32_e32 v31, 0xffff0000, v9
	s_waitcnt vmcnt(5)
	v_lshlrev_b32_e32 v32, 16, v36
	v_and_b32_e32 v33, 0xffff0000, v36
	v_lshlrev_b32_e32 v34, 16, v37
	v_and_b32_e32 v35, 0xffff0000, v37
	v_lshlrev_b32_e32 v36, 16, v38
	v_and_b32_e32 v37, 0xffff0000, v38
	v_lshlrev_b32_e32 v38, 16, v39
	v_and_b32_e32 v39, 0xffff0000, v39
	s_waitcnt vmcnt(4)
	v_lshlrev_b32_e32 v40, 16, v46
	v_and_b32_e32 v41, 0xffff0000, v46
	v_lshlrev_b32_e32 v42, 16, v47
	v_and_b32_e32 v43, 0xffff0000, v47
	v_lshlrev_b32_e32 v45, 16, v48
	v_and_b32_e32 v46, 0xffff0000, v48
	v_lshlrev_b32_e32 v47, 16, v49
	v_and_b32_e32 v48, 0xffff0000, v49
	s_waitcnt vmcnt(3)
	v_lshlrev_b32_e32 v49, 16, v54
	v_and_b32_e32 v51, 0xffff0000, v54
	v_lshlrev_b32_e32 v52, 16, v55
	v_and_b32_e32 v53, 0xffff0000, v55
	v_lshlrev_b32_e32 v54, 16, v56
	v_and_b32_e32 v55, 0xffff0000, v56
	v_lshlrev_b32_e32 v56, 16, v57
	v_and_b32_e32 v57, 0xffff0000, v57
	s_waitcnt vmcnt(2)
	v_lshlrev_b32_e32 v58, 16, v62
	v_and_b32_e32 v59, 0xffff0000, v62
	v_lshlrev_b32_e32 v60, 16, v63
	v_and_b32_e32 v61, 0xffff0000, v63
	v_lshlrev_b32_e32 v62, 16, v64
	v_and_b32_e32 v63, 0xffff0000, v64
	v_lshlrev_b32_e32 v64, 16, v65
	v_and_b32_e32 v65, 0xffff0000, v65
	s_waitcnt vmcnt(1)
	v_lshlrev_b32_e32 v66, 16, v68
	v_and_b32_e32 v67, 0xffff0000, v68
	v_lshlrev_b32_e32 v68, 16, v69
	v_and_b32_e32 v69, 0xffff0000, v69
	v_lshlrev_b32_e32 v2, 16, v70
	v_and_b32_e32 v3, 0xffff0000, v70
	v_lshlrev_b32_e32 v4, 16, v71
	v_and_b32_e32 v5, 0xffff0000, v71
	s_waitcnt vmcnt(0)
	ds_write_b128 v140, v[144:147]
	ds_write_b128 v140, v[148:151] offset:1024
	ds_write_b128 v140, v[152:155] offset:2048
	ds_write_b128 v140, v[156:159] offset:3072
	ds_write_b128 v140, v[160:163] offset:4096
	ds_write_b128 v140, v[164:167] offset:5120
	ds_write_b128 v140, v[168:171] offset:6144
	ds_write_b128 v140, v[172:175] offset:7168
	v_and_b32_e32 v141, 63, v254
	v_lshlrev_b32_e32 v141, 2, v141
	v_add_u32_e32 v143, v143, v141
	s_waitcnt lgkmcnt(0)
	ds_read_b32 v139, v143
	v_lshlrev_b32_e32 v6, 16, v72
	v_and_b32_e32 v7, 0xffff0000, v72
	v_lshlrev_b32_e32 v8, 16, v73
	v_and_b32_e32 v9, 0xffff0000, v73
	v_lshlrev_b32_e32 v10, 16, v74
	v_and_b32_e32 v11, 0xffff0000, v74
	v_lshlrev_b32_e32 v14, 16, v75
	v_and_b32_e32 v15, 0xffff0000, v75
	v_mov_b32_e32 v70, -1
	v_mov_b32_e32 v71, -1
	v_mov_b32_e32 v72, 0xff61b1e6
	v_mov_b32_e32 v73, 0xff61b1e6
; __device__ __forceinline__ void prep_phase(const Args& a, LAS unsigned char* lds, int tid, int lane, int wave) {
;     ...
;             for (int n = 0; n < blk; ++n) {
;                 const float* kb = KBAR + ((size_t)(bh * 32 + n)) * 64; float gsum = 0.f;
; #pragma unroll
;                 for (int d = 0; d < 64; ++d) gsum += q[d] * kb[d];
;                 if (gsum > g0) { g2 = g1; i2 = i1; g1 = g0; i1 = i0; g0 = gsum; i0 = n; }
;                 else if (gsum > g1) { g2 = g1; i2 = i1; g1 = gsum; i1 = n; }
;                 else if (gsum > g2) { g2 = gsum; i2 = n; }
;             }
.LBB0_561:
	s_waitcnt lgkmcnt(0)
	v_mov_b32_e32 v138, v139
	v_add_u32_e32 v143, 0x100, v143
	ds_read_b32 v139, v143
	v_readlane_b32 s99, v138, 0
	v_fma_f32 v74, s99, v1, 0
	v_readlane_b32 s98, v138, 1
	v_fmac_f32_e32 v74, s98, v17
	v_readlane_b32 s99, v138, 2
	v_fmac_f32_e32 v74, s99, v18
	v_readlane_b32 s98, v138, 3
	v_fmac_f32_e32 v74, s98, v19
	v_readlane_b32 s99, v138, 4
	v_fmac_f32_e32 v74, s99, v20
	v_readlane_b32 s98, v138, 5
	v_fmac_f32_e32 v74, s98, v21
	v_readlane_b32 s99, v138, 6
	v_fmac_f32_e32 v74, s99, v22
	v_readlane_b32 s98, v138, 7
	v_fmac_f32_e32 v74, s98, v23
	v_readlane_b32 s99, v138, 8
	v_fmac_f32_e32 v74, s99, v24
	v_readlane_b32 s98, v138, 9
	v_fmac_f32_e32 v74, s98, v25
	v_readlane_b32 s99, v138, 10
	v_fmac_f32_e32 v74, s99, v26
	v_readlane_b32 s98, v138, 11
	v_fmac_f32_e32 v74, s98, v27
	v_readlane_b32 s99, v138, 12
	v_fmac_f32_e32 v74, s99, v28
	v_readlane_b32 s98, v138, 13
	v_fmac_f32_e32 v74, s98, v29
	v_readlane_b32 s99, v138, 14
	v_fmac_f32_e32 v74, s99, v30
	v_readlane_b32 s98, v138, 15
	v_fmac_f32_e32 v74, s98, v31
	v_readlane_b32 s99, v138, 16
	v_fmac_f32_e32 v74, s99, v32
	v_readlane_b32 s98, v138, 17
	v_fmac_f32_e32 v74, s98, v33
	v_readlane_b32 s99, v138, 18
	v_fmac_f32_e32 v74, s99, v34
	v_readlane_b32 s98, v138, 19
	v_fmac_f32_e32 v74, s98, v35
	v_readlane_b32 s99, v138, 20
	v_fmac_f32_e32 v74, s99, v36
	v_readlane_b32 s98, v138, 21
	v_fmac_f32_e32 v74, s98, v37
	v_readlane_b32 s99, v138, 22
	v_fmac_f32_e32 v74, s99, v38
	v_readlane_b32 s98, v138, 23
	v_fmac_f32_e32 v74, s98, v39
	v_readlane_b32 s99, v138, 24
	v_fmac_f32_e32 v74, s99, v40
	v_readlane_b32 s98, v138, 25
	v_fmac_f32_e32 v74, s98, v41
	v_readlane_b32 s99, v138, 26
	v_fmac_f32_e32 v74, s99, v42
	v_readlane_b32 s98, v138, 27
	v_fmac_f32_e32 v74, s98, v43
	v_readlane_b32 s99, v138, 28
	v_fmac_f32_e32 v74, s99, v45
	v_readlane_b32 s98, v138, 29
	v_fmac_f32_e32 v74, s98, v46
	v_readlane_b32 s99, v138, 30
	v_fmac_f32_e32 v74, s99, v47
	v_readlane_b32 s98, v138, 31
	v_fmac_f32_e32 v74, s98, v48
	v_readlane_b32 s99, v138, 32
	v_fmac_f32_e32 v74, s99, v49
	v_readlane_b32 s98, v138, 33
	v_fmac_f32_e32 v74, s98, v51
	v_readlane_b32 s99, v138, 34
	v_fmac_f32_e32 v74, s99, v52
	v_readlane_b32 s98, v138, 35
	v_fmac_f32_e32 v74, s98, v53
	v_readlane_b32 s99, v138, 36
	v_fmac_f32_e32 v74, s99, v54
	v_readlane_b32 s98, v138, 37
	v_fmac_f32_e32 v74, s98, v55
	v_readlane_b32 s99, v138, 38
	v_fmac_f32_e32 v74, s99, v56
	v_readlane_b32 s98, v138, 39
	v_fmac_f32_e32 v74, s98, v57
	v_readlane_b32 s99, v138, 40
	v_fmac_f32_e32 v74, s99, v58
	v_readlane_b32 s98, v138, 41
	v_fmac_f32_e32 v74, s98, v59
	v_readlane_b32 s99, v138, 42
	v_fmac_f32_e32 v74, s99, v60
	v_readlane_b32 s98, v138, 43
	v_fmac_f32_e32 v74, s98, v61
	v_readlane_b32 s99, v138, 44
	v_fmac_f32_e32 v74, s99, v62
	v_readlane_b32 s98, v138, 45
	v_fmac_f32_e32 v74, s98, v63
	v_readlane_b32 s99, v138, 46
	v_fmac_f32_e32 v74, s99, v64
	v_readlane_b32 s98, v138, 47
	v_fmac_f32_e32 v74, s98, v65
	v_readlane_b32 s99, v138, 48
	v_fmac_f32_e32 v74, s99, v66
	v_readlane_b32 s98, v138, 49
	v_fmac_f32_e32 v74, s98, v67
	v_readlane_b32 s99, v138, 50
	v_fmac_f32_e32 v74, s99, v68
	v_readlane_b32 s98, v138, 52
	v_mul_f32_e32 v78, s98, v2
	v_readlane_b32 s99, v138, 53
	v_mul_f32_e32 v79, s99, v3
	v_readlane_b32 s98, v138, 51
	v_fmac_f32_e32 v74, s98, v69
	v_add_f32_e32 v74, v74, v78
	v_readlane_b32 s99, v138, 54
	v_mul_f32_e32 v80, s99, v4
	v_readlane_b32 s98, v138, 55
	v_mul_f32_e32 v81, s98, v5
	v_add_f32_e32 v74, v74, v79
	v_add_f32_e32 v74, v74, v80
	v_readlane_b32 s99, v138, 56
	v_mul_f32_e32 v82, s99, v6
	v_readlane_b32 s98, v138, 57
	v_mul_f32_e32 v83, s98, v7
	v_add_f32_e32 v74, v74, v81
	v_add_f32_e32 v74, v74, v82
	v_readlane_b32 s99, v138, 58
	v_mul_f32_e32 v84, s99, v8
	v_readlane_b32 s98, v138, 59
	v_mul_f32_e32 v85, s98, v9
	v_add_f32_e32 v74, v74, v83
	v_add_f32_e32 v74, v74, v84
	v_readlane_b32 s99, v138, 60
	v_mul_f32_e32 v86, s99, v10
	v_readlane_b32 s98, v138, 61
	v_mul_f32_e32 v87, s98, v11
	v_add_f32_e32 v74, v74, v85
	v_add_f32_e32 v74, v74, v86
	v_readlane_b32 s99, v138, 62
	v_mul_f32_e32 v88, s99, v14
	v_readlane_b32 s98, v138, 63
	v_mul_f32_e32 v89, s98, v15
	v_add_f32_e32 v74, v74, v87
	v_add_f32_e32 v74, v74, v88
	v_add_f32_e32 v74, v74, v89
	v_cmp_ngt_f32_e32 vcc, v74, v73
	v_mov_b32_e32 v75, s6
	s_and_saveexec_b64 s[26:27], vcc
	s_cbranch_execz .LBB0_567
	v_cmp_ngt_f32_e32 vcc, v74, v72
	v_mov_b32_e32 v76, s6
	s_and_saveexec_b64 s[28:29], vcc
	s_cbranch_execz .LBB0_566
	v_cmp_gt_f32_e32 vcc, v74, v50
	s_and_saveexec_b64 s[8:9], vcc
	v_mov_b32_e32 v44, s6
	v_mov_b32_e32 v50, v74
	s_or_b64 exec, exec, s[8:9]
	v_mov_b32_e32 v76, v70
	v_mov_b32_e32 v74, v72
	v_mov_b32_e32 v72, v50
	v_mov_b32_e32 v70, v44
